# hand-written row loop for the two modulate-norm phases: all loads of a row issued together, next row prefetched, split-K partial sums batched
# speedup vs baseline: 1.0206x; 1.0206x over previous
.LBB0_618:
	v_lshrrev_b32_e32 v210, 1, v176
	v_writelane_b32 v255, s83, 10
	v_writelane_b32 v255, s82, 11
	v_writelane_b32 v255, s85, 12
	v_writelane_b32 v255, s84, 13
	v_readfirstlane_b32 s8, v32
	v_readfirstlane_b32 s9, v33
	v_readfirstlane_b32 s10, v34
	v_readfirstlane_b32 s11, v35
	s_cmp_lg_u64 s[6:7], 0
	s_cselect_b32 s12, 1, 0
	s_mov_b32 s13, 0
	v_writelane_b32 v255, s8, 14
	v_writelane_b32 v255, s9, 15
	v_writelane_b32 v255, s10, 16
	v_writelane_b32 v255, s11, 17
	v_writelane_b32 v255, s12, 18
	v_writelane_b32 v255, s13, 19
	v_readfirstlane_b32 s10, v38
	v_readfirstlane_b32 s11, v39
	s_add_u32 s10, s10, 0x1000
	s_addc_u32 s11, s11, 0
	global_load_dwordx4 v[178:181], v176, s[10:11] offset:-4096
	global_load_dwordx4 v[182:185], v176, s[10:11] offset:-3072
	global_load_dwordx4 v[186:189], v176, s[10:11] offset:-2048
	global_load_dwordx4 v[190:193], v176, s[10:11] offset:-1024
	global_load_dwordx4 v[194:197], v176, s[10:11] offset:0
	global_load_dwordx4 v[198:201], v176, s[10:11] offset:1024
	global_load_dwordx4 v[202:205], v176, s[10:11] offset:2048
	global_load_dwordx4 v[206:209], v176, s[10:11] offset:3072
	s_sub_i32 s3, s2, s88
.Lnrm_p1_adv0:
	s_add_i32 s3, s3, s88
	s_cmpk_lt_i32 s3, 0x2400
	s_cbranch_scc0 .Lnrm_p1_first_done
.Lnrm_p1_first_done:
	s_cmpk_lt_i32 s3, 0x2400
	s_cbranch_scc0 .Lnrm_p1_exit
	s_mul_hi_i32 s12, s3, 0x38e38e39
	s_lshr_b32 s13, s12, 31
	s_ashr_i32 s12, s12, 9
	s_add_i32 s12, s12, s13
	s_mul_i32 s13, s12, 0xfffff700
	s_add_i32 s13, s3, s13
	s_cmpk_lt_i32 s13, 0x100
	s_cbranch_scc1 .Lnrm_p1_nxctx0
	v_readlane_b32 s14, v255, 10
	v_readlane_b32 s15, v255, 11
	s_lshl_b32 s12, s12, 11
	s_add_i32 s12, s12, s13
	s_addk_i32 s12, 0xff00
	s_branch .Lnrm_p1_nxcom0
.Lnrm_p1_nxctx0:
	v_readlane_b32 s14, v255, 12
	v_readlane_b32 s15, v255, 13
	s_lshl_b32 s12, s12, 8
	s_add_i32 s12, s12, s13
.Lnrm_p1_nxcom0:
	s_cmp_eq_u64 s[14:15], 0
	s_cbranch_scc0 .Lnrm_p1_nxhave0
	s_add_u32 s14, s54, 0xb600000
	s_addc_u32 s15, s55, 0
	s_mov_b32 s12, s3
.Lnrm_p1_nxhave0:
	s_lshl_b32 s12, s12, 13
	s_add_u32 s14, s14, s12
	s_addc_u32 s15, s15, 0
	s_add_u32 s14, s14, 0x1000
	s_addc_u32 s15, s15, 0
	global_load_dwordx4 v[64:67], v176, s[14:15] offset:-4096
	global_load_dwordx4 v[68:71], v176, s[14:15] offset:-3072
	global_load_dwordx4 v[72:75], v176, s[14:15] offset:-2048
	global_load_dwordx4 v[76:79], v176, s[14:15] offset:-1024
	global_load_dwordx4 v[80:83], v176, s[14:15] offset:0
	global_load_dwordx4 v[84:87], v176, s[14:15] offset:1024
	global_load_dwordx4 v[88:91], v176, s[14:15] offset:2048
	global_load_dwordx4 v[92:95], v176, s[14:15] offset:3072
	s_waitcnt vmcnt(0)
.Lnrm_p1_top:
	s_mov_b32 s2, s3
	v_mov_b64_e32 v[0:1], v[64:65]
	v_mov_b64_e32 v[2:3], v[66:67]
	v_mov_b64_e32 v[4:5], v[68:69]
	v_mov_b64_e32 v[6:7], v[70:71]
	v_mov_b64_e32 v[8:9], v[72:73]
	v_mov_b64_e32 v[10:11], v[74:75]
	v_mov_b64_e32 v[12:13], v[76:77]
	v_mov_b64_e32 v[14:15], v[78:79]
	v_mov_b64_e32 v[16:17], v[80:81]
	v_mov_b64_e32 v[18:19], v[82:83]
	v_mov_b64_e32 v[20:21], v[84:85]
	v_mov_b64_e32 v[22:23], v[86:87]
	v_mov_b64_e32 v[24:25], v[88:89]
	v_mov_b64_e32 v[26:27], v[90:91]
	v_mov_b64_e32 v[28:29], v[92:93]
	v_mov_b64_e32 v[30:31], v[94:95]
	s_mul_hi_i32 s4, s2, 0x38e38e39
	s_lshr_b32 s5, s4, 31
	s_ashr_i32 s4, s4, 9
	s_add_i32 s4, s4, s5
	s_mul_i32 s5, s4, 0xfffff700
	s_add_i32 s5, s2, s5
	s_cmpk_lt_i32 s5, 0x100
	s_cselect_b32 s100, 1, 0
	v_readlane_b32 s8, v255, 18
	s_and_b32 s8, s8, s100
	s_cmp_lg_u32 s8, 0
	s_cbranch_scc0 .Lnrm_p1_nopart
	v_readlane_b32 s12, v255, 14
	v_readlane_b32 s13, v255, 15
	s_lshl_b32 s8, s4, 8
	s_add_i32 s8, s8, s5
	s_lshl_b32 s8, s8, 13
	s_add_u32 s12, s12, s8
	s_addc_u32 s13, s13, 0
	s_add_u32 s12, s12, 0x1000
	s_addc_u32 s13, s13, 0
	v_readlane_b32 s10, v255, 16
	v_readlane_b32 s11, v255, 17
	s_nop 0
	s_add_u32 s10, s10, 0x1000
	s_addc_u32 s11, s11, 0
	s_lshl_b32 s8, s2, 13
	s_add_u32 s8, s8, 0xb601000
	s_add_u32 s8, s54, s8
	s_addc_u32 s9, s55, 0
	s_mov_b64 s[14:15], s[12:13]
	global_load_dwordx4 v[96:99], v176, s[14:15] offset:-4096
	global_load_dwordx4 v[128:131], v176, s[14:15] offset:-3072
	s_add_u32 s14, s14, 0x800000
	s_addc_u32 s15, s15, 0
	global_load_dwordx4 v[100:103], v176, s[14:15] offset:-4096
	global_load_dwordx4 v[132:135], v176, s[14:15] offset:-3072
	s_add_u32 s14, s14, 0x800000
	s_addc_u32 s15, s15, 0
	global_load_dwordx4 v[104:107], v176, s[14:15] offset:-4096
	global_load_dwordx4 v[136:139], v176, s[14:15] offset:-3072
	s_add_u32 s14, s14, 0x800000
	s_addc_u32 s15, s15, 0
	global_load_dwordx4 v[108:111], v176, s[14:15] offset:-4096
	global_load_dwordx4 v[140:143], v176, s[14:15] offset:-3072
	s_add_u32 s14, s14, 0x800000
	s_addc_u32 s15, s15, 0
	global_load_dwordx4 v[112:115], v176, s[14:15] offset:-4096
	global_load_dwordx4 v[144:147], v176, s[14:15] offset:-3072
	s_add_u32 s14, s14, 0x800000
	s_addc_u32 s15, s15, 0
	global_load_dwordx4 v[116:119], v176, s[14:15] offset:-4096
	global_load_dwordx4 v[148:151], v176, s[14:15] offset:-3072
	s_add_u32 s14, s14, 0x800000
	s_addc_u32 s15, s15, 0
	global_load_dwordx4 v[120:123], v176, s[14:15] offset:-4096
	global_load_dwordx4 v[152:155], v176, s[14:15] offset:-3072
	s_add_u32 s14, s14, 0x800000
	s_addc_u32 s15, s15, 0
	global_load_dwordx4 v[124:127], v176, s[14:15] offset:-4096
	global_load_dwordx4 v[156:159], v176, s[14:15] offset:-3072
	global_load_dwordx4 v[160:163], v176, s[10:11] offset:-4096
	global_load_dwordx4 v[164:167], v176, s[10:11] offset:-3072
	s_waitcnt vmcnt(0)
	v_pk_add_f32 v[96:97], v[96:97], v[100:101]
	v_pk_add_f32 v[98:99], v[98:99], v[102:103]
	v_pk_add_f32 v[96:97], v[96:97], v[104:105]
	v_pk_add_f32 v[98:99], v[98:99], v[106:107]
	v_pk_add_f32 v[96:97], v[96:97], v[108:109]
	v_pk_add_f32 v[98:99], v[98:99], v[110:111]
	v_pk_add_f32 v[96:97], v[96:97], v[112:113]
	v_pk_add_f32 v[98:99], v[98:99], v[114:115]
	v_pk_add_f32 v[96:97], v[96:97], v[116:117]
	v_pk_add_f32 v[98:99], v[98:99], v[118:119]
	v_pk_add_f32 v[96:97], v[96:97], v[120:121]
	v_pk_add_f32 v[98:99], v[98:99], v[122:123]
	v_pk_add_f32 v[96:97], v[96:97], v[124:125]
	v_pk_add_f32 v[98:99], v[98:99], v[126:127]
	v_pk_add_f32 v[128:129], v[128:129], v[132:133]
	v_pk_add_f32 v[130:131], v[130:131], v[134:135]
	v_pk_add_f32 v[128:129], v[128:129], v[136:137]
	v_pk_add_f32 v[130:131], v[130:131], v[138:139]
	v_pk_add_f32 v[128:129], v[128:129], v[140:141]
	v_pk_add_f32 v[130:131], v[130:131], v[142:143]
	v_pk_add_f32 v[128:129], v[128:129], v[144:145]
	v_pk_add_f32 v[130:131], v[130:131], v[146:147]
	v_pk_add_f32 v[128:129], v[128:129], v[148:149]
	v_pk_add_f32 v[130:131], v[130:131], v[150:151]
	v_pk_add_f32 v[128:129], v[128:129], v[152:153]
	v_pk_add_f32 v[130:131], v[130:131], v[154:155]
	v_pk_add_f32 v[128:129], v[128:129], v[156:157]
	v_pk_add_f32 v[130:131], v[130:131], v[158:159]
	v_pk_fma_f32 v[0:1], v[96:97], v[160:161], v[0:1]
	v_pk_fma_f32 v[2:3], v[98:99], v[162:163], v[2:3]
	v_pk_fma_f32 v[4:5], v[128:129], v[164:165], v[4:5]
	v_pk_fma_f32 v[6:7], v[130:131], v[166:167], v[6:7]
	global_store_dwordx4 v176, v[0:3], s[8:9] offset:-4096
	global_store_dwordx4 v176, v[4:7], s[8:9] offset:-3072
	s_mov_b64 s[14:15], s[12:13]
	global_load_dwordx4 v[96:99], v176, s[14:15] offset:-2048
	global_load_dwordx4 v[128:131], v176, s[14:15] offset:-1024
	s_add_u32 s14, s14, 0x800000
	s_addc_u32 s15, s15, 0
	global_load_dwordx4 v[100:103], v176, s[14:15] offset:-2048
	global_load_dwordx4 v[132:135], v176, s[14:15] offset:-1024
	s_add_u32 s14, s14, 0x800000
	s_addc_u32 s15, s15, 0
	global_load_dwordx4 v[104:107], v176, s[14:15] offset:-2048
	global_load_dwordx4 v[136:139], v176, s[14:15] offset:-1024
	s_add_u32 s14, s14, 0x800000
	s_addc_u32 s15, s15, 0
	global_load_dwordx4 v[108:111], v176, s[14:15] offset:-2048
	global_load_dwordx4 v[140:143], v176, s[14:15] offset:-1024
	s_add_u32 s14, s14, 0x800000
	s_addc_u32 s15, s15, 0
	global_load_dwordx4 v[112:115], v176, s[14:15] offset:-2048
	global_load_dwordx4 v[144:147], v176, s[14:15] offset:-1024
	s_add_u32 s14, s14, 0x800000
	s_addc_u32 s15, s15, 0
	global_load_dwordx4 v[116:119], v176, s[14:15] offset:-2048
	global_load_dwordx4 v[148:151], v176, s[14:15] offset:-1024
	s_add_u32 s14, s14, 0x800000
	s_addc_u32 s15, s15, 0
	global_load_dwordx4 v[120:123], v176, s[14:15] offset:-2048
	global_load_dwordx4 v[152:155], v176, s[14:15] offset:-1024
	s_add_u32 s14, s14, 0x800000
	s_addc_u32 s15, s15, 0
	global_load_dwordx4 v[124:127], v176, s[14:15] offset:-2048
	global_load_dwordx4 v[156:159], v176, s[14:15] offset:-1024
	global_load_dwordx4 v[160:163], v176, s[10:11] offset:-2048
	global_load_dwordx4 v[164:167], v176, s[10:11] offset:-1024
	s_waitcnt vmcnt(0)
	v_pk_add_f32 v[96:97], v[96:97], v[100:101]
	v_pk_add_f32 v[98:99], v[98:99], v[102:103]
	v_pk_add_f32 v[96:97], v[96:97], v[104:105]
	v_pk_add_f32 v[98:99], v[98:99], v[106:107]
	v_pk_add_f32 v[96:97], v[96:97], v[108:109]
	v_pk_add_f32 v[98:99], v[98:99], v[110:111]
	v_pk_add_f32 v[96:97], v[96:97], v[112:113]
	v_pk_add_f32 v[98:99], v[98:99], v[114:115]
	v_pk_add_f32 v[96:97], v[96:97], v[116:117]
	v_pk_add_f32 v[98:99], v[98:99], v[118:119]
	v_pk_add_f32 v[96:97], v[96:97], v[120:121]
	v_pk_add_f32 v[98:99], v[98:99], v[122:123]
	v_pk_add_f32 v[96:97], v[96:97], v[124:125]
	v_pk_add_f32 v[98:99], v[98:99], v[126:127]
	v_pk_add_f32 v[128:129], v[128:129], v[132:133]
	v_pk_add_f32 v[130:131], v[130:131], v[134:135]
	v_pk_add_f32 v[128:129], v[128:129], v[136:137]
	v_pk_add_f32 v[130:131], v[130:131], v[138:139]
	v_pk_add_f32 v[128:129], v[128:129], v[140:141]
	v_pk_add_f32 v[130:131], v[130:131], v[142:143]
	v_pk_add_f32 v[128:129], v[128:129], v[144:145]
	v_pk_add_f32 v[130:131], v[130:131], v[146:147]
	v_pk_add_f32 v[128:129], v[128:129], v[148:149]
	v_pk_add_f32 v[130:131], v[130:131], v[150:151]
	v_pk_add_f32 v[128:129], v[128:129], v[152:153]
	v_pk_add_f32 v[130:131], v[130:131], v[154:155]
	v_pk_add_f32 v[128:129], v[128:129], v[156:157]
	v_pk_add_f32 v[130:131], v[130:131], v[158:159]
	v_pk_fma_f32 v[8:9], v[96:97], v[160:161], v[8:9]
	v_pk_fma_f32 v[10:11], v[98:99], v[162:163], v[10:11]
	v_pk_fma_f32 v[12:13], v[128:129], v[164:165], v[12:13]
	v_pk_fma_f32 v[14:15], v[130:131], v[166:167], v[14:15]
	global_store_dwordx4 v176, v[8:11], s[8:9] offset:-2048
	global_store_dwordx4 v176, v[12:15], s[8:9] offset:-1024
	s_mov_b64 s[14:15], s[12:13]
	global_load_dwordx4 v[96:99], v176, s[14:15] offset:0
	global_load_dwordx4 v[128:131], v176, s[14:15] offset:1024
	s_add_u32 s14, s14, 0x800000
	s_addc_u32 s15, s15, 0
	global_load_dwordx4 v[100:103], v176, s[14:15] offset:0
	global_load_dwordx4 v[132:135], v176, s[14:15] offset:1024
	s_add_u32 s14, s14, 0x800000
	s_addc_u32 s15, s15, 0
	global_load_dwordx4 v[104:107], v176, s[14:15] offset:0
	global_load_dwordx4 v[136:139], v176, s[14:15] offset:1024
	s_add_u32 s14, s14, 0x800000
	s_addc_u32 s15, s15, 0
	global_load_dwordx4 v[108:111], v176, s[14:15] offset:0
	global_load_dwordx4 v[140:143], v176, s[14:15] offset:1024
	s_add_u32 s14, s14, 0x800000
	s_addc_u32 s15, s15, 0
	global_load_dwordx4 v[112:115], v176, s[14:15] offset:0
	global_load_dwordx4 v[144:147], v176, s[14:15] offset:1024
	s_add_u32 s14, s14, 0x800000
	s_addc_u32 s15, s15, 0
	global_load_dwordx4 v[116:119], v176, s[14:15] offset:0
	global_load_dwordx4 v[148:151], v176, s[14:15] offset:1024
	s_add_u32 s14, s14, 0x800000
	s_addc_u32 s15, s15, 0
	global_load_dwordx4 v[120:123], v176, s[14:15] offset:0
	global_load_dwordx4 v[152:155], v176, s[14:15] offset:1024
	s_add_u32 s14, s14, 0x800000
	s_addc_u32 s15, s15, 0
	global_load_dwordx4 v[124:127], v176, s[14:15] offset:0
	global_load_dwordx4 v[156:159], v176, s[14:15] offset:1024
	global_load_dwordx4 v[160:163], v176, s[10:11] offset:0
	global_load_dwordx4 v[164:167], v176, s[10:11] offset:1024
	s_waitcnt vmcnt(0)
	v_pk_add_f32 v[96:97], v[96:97], v[100:101]
	v_pk_add_f32 v[98:99], v[98:99], v[102:103]
	v_pk_add_f32 v[96:97], v[96:97], v[104:105]
	v_pk_add_f32 v[98:99], v[98:99], v[106:107]
	v_pk_add_f32 v[96:97], v[96:97], v[108:109]
	v_pk_add_f32 v[98:99], v[98:99], v[110:111]
	v_pk_add_f32 v[96:97], v[96:97], v[112:113]
	v_pk_add_f32 v[98:99], v[98:99], v[114:115]
	v_pk_add_f32 v[96:97], v[96:97], v[116:117]
	v_pk_add_f32 v[98:99], v[98:99], v[118:119]
	v_pk_add_f32 v[96:97], v[96:97], v[120:121]
	v_pk_add_f32 v[98:99], v[98:99], v[122:123]
	v_pk_add_f32 v[96:97], v[96:97], v[124:125]
	v_pk_add_f32 v[98:99], v[98:99], v[126:127]
	v_pk_add_f32 v[128:129], v[128:129], v[132:133]
	v_pk_add_f32 v[130:131], v[130:131], v[134:135]
	v_pk_add_f32 v[128:129], v[128:129], v[136:137]
	v_pk_add_f32 v[130:131], v[130:131], v[138:139]
	v_pk_add_f32 v[128:129], v[128:129], v[140:141]
	v_pk_add_f32 v[130:131], v[130:131], v[142:143]
	v_pk_add_f32 v[128:129], v[128:129], v[144:145]
	v_pk_add_f32 v[130:131], v[130:131], v[146:147]
	v_pk_add_f32 v[128:129], v[128:129], v[148:149]
	v_pk_add_f32 v[130:131], v[130:131], v[150:151]
	v_pk_add_f32 v[128:129], v[128:129], v[152:153]
	v_pk_add_f32 v[130:131], v[130:131], v[154:155]
	v_pk_add_f32 v[128:129], v[128:129], v[156:157]
	v_pk_add_f32 v[130:131], v[130:131], v[158:159]
	v_pk_fma_f32 v[16:17], v[96:97], v[160:161], v[16:17]
	v_pk_fma_f32 v[18:19], v[98:99], v[162:163], v[18:19]
	v_pk_fma_f32 v[20:21], v[128:129], v[164:165], v[20:21]
	v_pk_fma_f32 v[22:23], v[130:131], v[166:167], v[22:23]
	global_store_dwordx4 v176, v[16:19], s[8:9] offset:0
	global_store_dwordx4 v176, v[20:23], s[8:9] offset:1024
	s_mov_b64 s[14:15], s[12:13]
	global_load_dwordx4 v[96:99], v176, s[14:15] offset:2048
	global_load_dwordx4 v[128:131], v176, s[14:15] offset:3072
	s_add_u32 s14, s14, 0x800000
	s_addc_u32 s15, s15, 0
	global_load_dwordx4 v[100:103], v176, s[14:15] offset:2048
	global_load_dwordx4 v[132:135], v176, s[14:15] offset:3072
	s_add_u32 s14, s14, 0x800000
	s_addc_u32 s15, s15, 0
	global_load_dwordx4 v[104:107], v176, s[14:15] offset:2048
	global_load_dwordx4 v[136:139], v176, s[14:15] offset:3072
	s_add_u32 s14, s14, 0x800000
	s_addc_u32 s15, s15, 0
	global_load_dwordx4 v[108:111], v176, s[14:15] offset:2048
	global_load_dwordx4 v[140:143], v176, s[14:15] offset:3072
	s_add_u32 s14, s14, 0x800000
	s_addc_u32 s15, s15, 0
	global_load_dwordx4 v[112:115], v176, s[14:15] offset:2048
	global_load_dwordx4 v[144:147], v176, s[14:15] offset:3072
	s_add_u32 s14, s14, 0x800000
	s_addc_u32 s15, s15, 0
	global_load_dwordx4 v[116:119], v176, s[14:15] offset:2048
	global_load_dwordx4 v[148:151], v176, s[14:15] offset:3072
	s_add_u32 s14, s14, 0x800000
	s_addc_u32 s15, s15, 0
	global_load_dwordx4 v[120:123], v176, s[14:15] offset:2048
	global_load_dwordx4 v[152:155], v176, s[14:15] offset:3072
	s_add_u32 s14, s14, 0x800000
	s_addc_u32 s15, s15, 0
	global_load_dwordx4 v[124:127], v176, s[14:15] offset:2048
	global_load_dwordx4 v[156:159], v176, s[14:15] offset:3072
	global_load_dwordx4 v[160:163], v176, s[10:11] offset:2048
	global_load_dwordx4 v[164:167], v176, s[10:11] offset:3072
	s_waitcnt vmcnt(0)
	v_pk_add_f32 v[96:97], v[96:97], v[100:101]
	v_pk_add_f32 v[98:99], v[98:99], v[102:103]
	v_pk_add_f32 v[96:97], v[96:97], v[104:105]
	v_pk_add_f32 v[98:99], v[98:99], v[106:107]
	v_pk_add_f32 v[96:97], v[96:97], v[108:109]
	v_pk_add_f32 v[98:99], v[98:99], v[110:111]
	v_pk_add_f32 v[96:97], v[96:97], v[112:113]
	v_pk_add_f32 v[98:99], v[98:99], v[114:115]
	v_pk_add_f32 v[96:97], v[96:97], v[116:117]
	v_pk_add_f32 v[98:99], v[98:99], v[118:119]
	v_pk_add_f32 v[96:97], v[96:97], v[120:121]
	v_pk_add_f32 v[98:99], v[98:99], v[122:123]
	v_pk_add_f32 v[96:97], v[96:97], v[124:125]
	v_pk_add_f32 v[98:99], v[98:99], v[126:127]
	v_pk_add_f32 v[128:129], v[128:129], v[132:133]
	v_pk_add_f32 v[130:131], v[130:131], v[134:135]
	v_pk_add_f32 v[128:129], v[128:129], v[136:137]
	v_pk_add_f32 v[130:131], v[130:131], v[138:139]
	v_pk_add_f32 v[128:129], v[128:129], v[140:141]
	v_pk_add_f32 v[130:131], v[130:131], v[142:143]
	v_pk_add_f32 v[128:129], v[128:129], v[144:145]
	v_pk_add_f32 v[130:131], v[130:131], v[146:147]
	v_pk_add_f32 v[128:129], v[128:129], v[148:149]
	v_pk_add_f32 v[130:131], v[130:131], v[150:151]
	v_pk_add_f32 v[128:129], v[128:129], v[152:153]
	v_pk_add_f32 v[130:131], v[130:131], v[154:155]
	v_pk_add_f32 v[128:129], v[128:129], v[156:157]
	v_pk_add_f32 v[130:131], v[130:131], v[158:159]
	v_pk_fma_f32 v[24:25], v[96:97], v[160:161], v[24:25]
	v_pk_fma_f32 v[26:27], v[98:99], v[162:163], v[26:27]
	v_pk_fma_f32 v[28:29], v[128:129], v[164:165], v[28:29]
	v_pk_fma_f32 v[30:31], v[130:131], v[166:167], v[30:31]
	global_store_dwordx4 v176, v[24:27], s[8:9] offset:2048
	global_store_dwordx4 v176, v[28:31], s[8:9] offset:3072
.Lnrm_p1_nopart:
	s_cmp_lg_u32 s100, 0
	s_cselect_b32 s8, 4, s4
	v_readlane_b32 s10, v254, 53
	v_readlane_b32 s11, v254, 54
	s_mul_i32 s8, s8, 0xc000
	s_add_u32 s10, s10, s8
	s_addc_u32 s11, s11, 0
	s_add_u32 s12, s10, 0x1000
	s_addc_u32 s13, s11, 0
	global_load_dwordx4 v[96:99], v176, s[12:13] offset:-4096
	global_load_dwordx4 v[100:103], v176, s[12:13] offset:-3072
	global_load_dwordx4 v[104:107], v176, s[12:13] offset:-2048
	global_load_dwordx4 v[108:111], v176, s[12:13] offset:-1024
	global_load_dwordx4 v[112:115], v176, s[12:13] offset:0
	global_load_dwordx4 v[116:119], v176, s[12:13] offset:1024
	global_load_dwordx4 v[120:123], v176, s[12:13] offset:2048
	global_load_dwordx4 v[124:127], v176, s[12:13] offset:3072
	s_add_u32 s12, s10, 0x3000
	s_addc_u32 s13, s11, 0
	global_load_dwordx4 v[128:131], v176, s[12:13] offset:-4096
	global_load_dwordx4 v[132:135], v176, s[12:13] offset:-3072
	global_load_dwordx4 v[136:139], v176, s[12:13] offset:-2048
	global_load_dwordx4 v[140:143], v176, s[12:13] offset:-1024
	global_load_dwordx4 v[144:147], v176, s[12:13] offset:0
	global_load_dwordx4 v[148:151], v176, s[12:13] offset:1024
	global_load_dwordx4 v[152:155], v176, s[12:13] offset:2048
	global_load_dwordx4 v[156:159], v176, s[12:13] offset:3072
	s_mov_b32 s3, s2

.Lnrm_p1_nxhave1:
	s_lshl_b32 s12, s12, 13
	s_add_u32 s14, s14, s12
	s_addc_u32 s15, s15, 0
	s_add_u32 s14, s14, 0x1000
	s_addc_u32 s15, s15, 0
	global_load_dwordx4 v[64:67], v176, s[14:15] offset:-4096
	global_load_dwordx4 v[68:71], v176, s[14:15] offset:-3072
	global_load_dwordx4 v[72:75], v176, s[14:15] offset:-2048
	global_load_dwordx4 v[76:79], v176, s[14:15] offset:-1024
	global_load_dwordx4 v[80:83], v176, s[14:15] offset:0
	global_load_dwordx4 v[84:87], v176, s[14:15] offset:1024
	global_load_dwordx4 v[88:91], v176, s[14:15] offset:2048
	global_load_dwordx4 v[92:95], v176, s[14:15] offset:3072
.Lnrm_p1_nonext:
	v_mul_f32_e32 v160, v0, v0
	v_mul_f32_e32 v161, v1, v1
	v_mul_f32_e32 v162, v2, v2
	v_mul_f32_e32 v163, v3, v3
	v_fmac_f32_e32 v160, v4, v4
	v_fmac_f32_e32 v161, v5, v5
	v_fmac_f32_e32 v162, v6, v6
	v_fmac_f32_e32 v163, v7, v7
	v_fmac_f32_e32 v160, v8, v8
	v_fmac_f32_e32 v161, v9, v9
	v_fmac_f32_e32 v162, v10, v10
	v_fmac_f32_e32 v163, v11, v11
	v_fmac_f32_e32 v160, v12, v12
	v_fmac_f32_e32 v161, v13, v13
	v_fmac_f32_e32 v162, v14, v14
	v_fmac_f32_e32 v163, v15, v15
	v_fmac_f32_e32 v160, v16, v16
	v_fmac_f32_e32 v161, v17, v17
	v_fmac_f32_e32 v162, v18, v18
	v_fmac_f32_e32 v163, v19, v19
	v_fmac_f32_e32 v160, v20, v20
	v_fmac_f32_e32 v161, v21, v21
	v_fmac_f32_e32 v162, v22, v22
	v_fmac_f32_e32 v163, v23, v23
	v_fmac_f32_e32 v160, v24, v24
	v_fmac_f32_e32 v161, v25, v25
	v_fmac_f32_e32 v162, v26, v26
	v_fmac_f32_e32 v163, v27, v27
	v_fmac_f32_e32 v160, v28, v28
	v_fmac_f32_e32 v161, v29, v29
	v_fmac_f32_e32 v162, v30, v30
	v_fmac_f32_e32 v163, v31, v31
	v_add_f32_e32 v160, v160, v161
	v_add_f32_e32 v162, v162, v163
	v_add_f32_e32 v160, v160, v162
	s_nop 1
	v_add_f32_dpp v160, v160, v160 quad_perm:[1,0,3,2] row_mask:0xf bank_mask:0xf
	s_nop 1
	v_add_f32_dpp v160, v160, v160 quad_perm:[2,3,0,1] row_mask:0xf bank_mask:0xf
	s_nop 1
	v_add_f32_dpp v160, v160, v160 row_half_mirror row_mask:0xf bank_mask:0xf
	s_nop 1
	v_add_f32_dpp v160, v160, v160 row_mirror row_mask:0xf bank_mask:0xf
	s_nop 1
	v_mov_b32_e32 v161, v160
	s_nop 1
	v_permlane16_swap_b32_e32 v160, v161
	s_nop 1
	v_add_f32_e32 v160, v160, v161
	v_mov_b32_e32 v161, v160
	s_nop 1
	v_permlane32_swap_b32_e32 v160, v161
	s_nop 1
	v_add_f32_e32 v164, v160, v161
	v_fmamk_f32 v164, v164, 0x3a000000, v215
	v_mul_f32_e32 v165, 0x4f800000, v164
	v_cmp_gt_f32_e32 vcc, 0xf800000, v164
	s_nop 1
	v_cndmask_b32_e32 v164, v164, v165, vcc
	v_sqrt_f32_e32 v165, v164
	s_nop 0
	v_add_u32_e32 v166, -1, v165
	v_fma_f32 v167, -v166, v165, v164
	v_cmp_ge_f32_e64 s[14:15], 0, v167
	v_add_u32_e32 v167, 1, v165
	s_nop 0
	v_cndmask_b32_e64 v166, v165, v166, s[14:15]
	v_fma_f32 v165, -v167, v165, v164
	v_cmp_lt_f32_e64 s[14:15], 0, v165
	s_nop 1
	v_cndmask_b32_e64 v165, v166, v167, s[14:15]
	v_mul_f32_e32 v166, 0x37800000, v165
	v_cndmask_b32_e32 v165, v165, v166, vcc
	v_cmp_class_f32_e32 vcc, v164, v216
	s_nop 1
	v_cndmask_b32_e32 v164, v165, v164, vcc
	v_div_scale_f32 v165, s[14:15], v164, v164, 1.0
	v_rcp_f32_e32 v166, v165
	s_nop 1
	v_fma_f32 v167, -v165, v166, 1.0
	v_fmac_f32_e32 v166, v167, v166
	v_div_scale_f32 v167, vcc, 1.0, v164, 1.0
	v_mul_f32_e32 v168, v167, v166
	v_fma_f32 v169, -v165, v168, v167
	v_fmac_f32_e32 v168, v169, v166
	v_fma_f32 v165, -v165, v168, v167
	s_nop 0
	v_div_fmas_f32 v165, v165, v166, v168
	v_div_fixup_f32 v164, v165, v164, 1.0
	v_pk_mul_f32 v[0:1], v[0:1], v[164:165] op_sel_hi:[1,0]
	v_pk_mul_f32 v[2:3], v[2:3], v[164:165] op_sel_hi:[1,0]
	v_pk_mul_f32 v[4:5], v[4:5], v[164:165] op_sel_hi:[1,0]
	v_pk_mul_f32 v[6:7], v[6:7], v[164:165] op_sel_hi:[1,0]
	v_pk_mul_f32 v[8:9], v[8:9], v[164:165] op_sel_hi:[1,0]
	v_pk_mul_f32 v[10:11], v[10:11], v[164:165] op_sel_hi:[1,0]
	v_pk_mul_f32 v[12:13], v[12:13], v[164:165] op_sel_hi:[1,0]
	v_pk_mul_f32 v[14:15], v[14:15], v[164:165] op_sel_hi:[1,0]
	v_pk_mul_f32 v[16:17], v[16:17], v[164:165] op_sel_hi:[1,0]
	v_pk_mul_f32 v[18:19], v[18:19], v[164:165] op_sel_hi:[1,0]
	v_pk_mul_f32 v[20:21], v[20:21], v[164:165] op_sel_hi:[1,0]
	v_pk_mul_f32 v[22:23], v[22:23], v[164:165] op_sel_hi:[1,0]
	v_pk_mul_f32 v[24:25], v[24:25], v[164:165] op_sel_hi:[1,0]
	v_pk_mul_f32 v[26:27], v[26:27], v[164:165] op_sel_hi:[1,0]
	v_pk_mul_f32 v[28:29], v[28:29], v[164:165] op_sel_hi:[1,0]
	v_pk_mul_f32 v[30:31], v[30:31], v[164:165] op_sel_hi:[1,0]
	s_lshl_b32 s8, s2, 12
	s_add_u32 s8, s8, 0xfe00000
	s_add_u32 s8, s54, s8
	s_addc_u32 s9, s55, 0
	s_cmpk_lt_i32 s3, 0x2400
	s_cbranch_scc1 .Lnrm_p1_w8
	s_waitcnt vmcnt(0)
	s_branch .Lnrm_p1_wd
.Lnrm_p1_w8:
	s_waitcnt vmcnt(8)
.Lnrm_p1_wd:
	v_pk_mul_f32 v[0:1], v[178:179], v[0:1]
	v_pk_add_f32 v[172:173], v[128:129], 1.0 op_sel_hi:[1,0]
	v_pk_fma_f32 v[0:1], v[172:173], v[0:1], v[96:97]
	v_pk_mul_f32 v[2:3], v[180:181], v[2:3]
	v_pk_add_f32 v[174:175], v[130:131], 1.0 op_sel_hi:[1,0]
	v_pk_fma_f32 v[2:3], v[174:175], v[2:3], v[98:99]
	v_cvt_pk_bf16_f32 v168, v0, v1
	v_cvt_pk_bf16_f32 v169, v2, v3
	global_store_dwordx2 v210, v[168:169], s[8:9] offset:0
	s_nop 0
	v_pk_mul_f32 v[4:5], v[182:183], v[4:5]
	v_pk_add_f32 v[172:173], v[132:133], 1.0 op_sel_hi:[1,0]
	v_pk_fma_f32 v[4:5], v[172:173], v[4:5], v[100:101]
	v_pk_mul_f32 v[6:7], v[184:185], v[6:7]
	v_pk_add_f32 v[174:175], v[134:135], 1.0 op_sel_hi:[1,0]
	v_pk_fma_f32 v[6:7], v[174:175], v[6:7], v[102:103]
	v_cvt_pk_bf16_f32 v168, v4, v5
	v_cvt_pk_bf16_f32 v169, v6, v7
	global_store_dwordx2 v210, v[168:169], s[8:9] offset:512
	s_nop 0
	v_pk_mul_f32 v[8:9], v[186:187], v[8:9]
	v_pk_add_f32 v[172:173], v[136:137], 1.0 op_sel_hi:[1,0]
	v_pk_fma_f32 v[8:9], v[172:173], v[8:9], v[104:105]
	v_pk_mul_f32 v[10:11], v[188:189], v[10:11]
	v_pk_add_f32 v[174:175], v[138:139], 1.0 op_sel_hi:[1,0]
	v_pk_fma_f32 v[10:11], v[174:175], v[10:11], v[106:107]
	v_cvt_pk_bf16_f32 v168, v8, v9
	v_cvt_pk_bf16_f32 v169, v10, v11
	global_store_dwordx2 v210, v[168:169], s[8:9] offset:1024
	s_nop 0
	v_pk_mul_f32 v[12:13], v[190:191], v[12:13]
	v_pk_add_f32 v[172:173], v[140:141], 1.0 op_sel_hi:[1,0]
	v_pk_fma_f32 v[12:13], v[172:173], v[12:13], v[108:109]
	v_pk_mul_f32 v[14:15], v[192:193], v[14:15]
	v_pk_add_f32 v[174:175], v[142:143], 1.0 op_sel_hi:[1,0]
	v_pk_fma_f32 v[14:15], v[174:175], v[14:15], v[110:111]
	v_cvt_pk_bf16_f32 v168, v12, v13
	v_cvt_pk_bf16_f32 v169, v14, v15
	global_store_dwordx2 v210, v[168:169], s[8:9] offset:1536
	s_nop 0
	v_pk_mul_f32 v[16:17], v[194:195], v[16:17]
	v_pk_add_f32 v[172:173], v[144:145], 1.0 op_sel_hi:[1,0]
	v_pk_fma_f32 v[16:17], v[172:173], v[16:17], v[112:113]
	v_pk_mul_f32 v[18:19], v[196:197], v[18:19]
	v_pk_add_f32 v[174:175], v[146:147], 1.0 op_sel_hi:[1,0]
	v_pk_fma_f32 v[18:19], v[174:175], v[18:19], v[114:115]
	v_cvt_pk_bf16_f32 v168, v16, v17
	v_cvt_pk_bf16_f32 v169, v18, v19
	global_store_dwordx2 v210, v[168:169], s[8:9] offset:2048
	s_nop 0
	v_pk_mul_f32 v[20:21], v[198:199], v[20:21]
	v_pk_add_f32 v[172:173], v[148:149], 1.0 op_sel_hi:[1,0]
	v_pk_fma_f32 v[20:21], v[172:173], v[20:21], v[116:117]
	v_pk_mul_f32 v[22:23], v[200:201], v[22:23]
	v_pk_add_f32 v[174:175], v[150:151], 1.0 op_sel_hi:[1,0]
	v_pk_fma_f32 v[22:23], v[174:175], v[22:23], v[118:119]
	v_cvt_pk_bf16_f32 v168, v20, v21
	v_cvt_pk_bf16_f32 v169, v22, v23
	global_store_dwordx2 v210, v[168:169], s[8:9] offset:2560
	s_nop 0
	v_pk_mul_f32 v[24:25], v[202:203], v[24:25]
	v_pk_add_f32 v[172:173], v[152:153], 1.0 op_sel_hi:[1,0]
	v_pk_fma_f32 v[24:25], v[172:173], v[24:25], v[120:121]
	v_pk_mul_f32 v[26:27], v[204:205], v[26:27]
	v_pk_add_f32 v[174:175], v[154:155], 1.0 op_sel_hi:[1,0]
	v_pk_fma_f32 v[26:27], v[174:175], v[26:27], v[122:123]
	v_cvt_pk_bf16_f32 v168, v24, v25
	v_cvt_pk_bf16_f32 v169, v26, v27
	global_store_dwordx2 v210, v[168:169], s[8:9] offset:3072
	s_nop 0
	v_pk_mul_f32 v[28:29], v[206:207], v[28:29]
	v_pk_add_f32 v[172:173], v[156:157], 1.0 op_sel_hi:[1,0]
	v_pk_fma_f32 v[28:29], v[172:173], v[28:29], v[124:125]
	v_pk_mul_f32 v[30:31], v[208:209], v[30:31]
	v_pk_add_f32 v[174:175], v[158:159], 1.0 op_sel_hi:[1,0]
	v_pk_fma_f32 v[30:31], v[174:175], v[30:31], v[126:127]
	v_cvt_pk_bf16_f32 v168, v28, v29
	v_cvt_pk_bf16_f32 v169, v30, v31
	global_store_dwordx2 v210, v[168:169], s[8:9] offset:3584
	s_nop 0
	s_cmpk_lt_i32 s3, 0x2400
	s_cbranch_scc0 .Lnrm_p1_exit
	s_waitcnt vmcnt(8)
	s_branch .Lnrm_p1_top
.Lnrm_p1_exit:
.LBB0_620:
	s_waitcnt vmcnt(0)
	s_barrier
	s_mov_b64 s[2:3], exec
	v_readlane_b32 s4, v253, 42
	v_readlane_b32 s5, v253, 43
	s_and_b64 s[4:5], s[2:3], s[4:5]
	s_mov_b64 exec, s[4:5]
	s_cbranch_execz .LBB0_664
	v_readlane_b32 s36, v253, 39
	v_readlane_b32 s4, v254, 44
	v_readlane_b32 s37, v253, 40
	v_readlane_b32 s33, v253, 41
	v_mov_b32_e32 v0, s4
	s_waitcnt vmcnt(0) expcnt(0) lgkmcnt(0)
	ds_read_b32 v2, v0
	v_readlane_b32 s4, v254, 45
	s_waitcnt lgkmcnt(0)
	v_cmp_ne_u32_e32 vcc, 0, v2
	v_mov_b32_e32 v0, s4
	ds_read_b32 v0, v0
	s_cbranch_vccnz .LBB0_635
	s_add_u32 s4, s36, 0x1000
	s_addc_u32 s5, s37, 0
	s_add_u32 s6, s36, 0x1100
	s_addc_u32 s7, s37, 0
	s_add_u32 s8, s36, 0x1200
	s_addc_u32 s9, s37, 0
	s_add_u32 s10, s36, 0x1300
	s_addc_u32 s11, s37, 0
	s_mov_b32 s30, 1
	s_mov_b64 s[12:13], 0
	s_branch .LBB0_625

.LBB0_1322:
	v_lshrrev_b32_e32 v210, 1, v176
	v_readlane_b32 s8, v254, 57
	v_readlane_b32 s9, v254, 58
	v_readlane_b32 s10, v253, 11
	v_readlane_b32 s11, v253, 12
	s_cmp_lg_u64 s[8:9], 0
	s_cselect_b32 s12, 1, 0
	s_cselect_b32 s10, s10, 0
	s_cselect_b32 s11, s11, 0
	s_mov_b32 s13, 0
	v_writelane_b32 v255, s13, 10
	v_writelane_b32 v255, s13, 11
	v_writelane_b32 v255, s10, 12
	v_writelane_b32 v255, s11, 13
	s_cmp_lg_u64 s[78:79], 0
	s_cselect_b32 s13, 1, 0
	v_readfirstlane_b32 s8, v32
	v_readfirstlane_b32 s9, v33
	v_readfirstlane_b32 s10, v36
	v_readfirstlane_b32 s11, v37
	v_writelane_b32 v255, s8, 14
	v_writelane_b32 v255, s9, 15
	v_writelane_b32 v255, s10, 16
	v_writelane_b32 v255, s11, 17
	v_writelane_b32 v255, s12, 18
	v_writelane_b32 v255, s13, 19
	v_readfirstlane_b32 s10, v38
	v_readfirstlane_b32 s11, v39
	s_add_u32 s10, s10, 0x1000
	s_addc_u32 s11, s11, 0
	global_load_dwordx4 v[178:181], v176, s[10:11] offset:-4096
	global_load_dwordx4 v[182:185], v176, s[10:11] offset:-3072
	global_load_dwordx4 v[186:189], v176, s[10:11] offset:-2048
	global_load_dwordx4 v[190:193], v176, s[10:11] offset:-1024
	global_load_dwordx4 v[194:197], v176, s[10:11] offset:0
	global_load_dwordx4 v[198:201], v176, s[10:11] offset:1024
	global_load_dwordx4 v[202:205], v176, s[10:11] offset:2048
	global_load_dwordx4 v[206:209], v176, s[10:11] offset:3072
	s_sub_i32 s3, s2, s88
.Lnrm_p7_adv0:
	s_add_i32 s3, s3, s88
	s_cmpk_lt_i32 s3, 0x2400
	s_cbranch_scc0 .Lnrm_p7_first_done
	v_readlane_b32 s12, v255, 19
	s_cmp_eq_u32 s12, 0
	s_cbranch_scc1 .Lnrm_p7_first_done
	s_mul_hi_i32 s12, s3, 0x38e38e39
	s_lshr_b32 s13, s12, 31
	s_ashr_i32 s12, s12, 9
	s_add_i32 s12, s12, s13
	s_mul_i32 s13, s12, 0xfffff700
	s_add_i32 s13, s3, s13
	s_cmpk_lt_i32 s13, 0x100
	s_cbranch_scc1 .Lnrm_p7_adv0

.Lnrm_p7_nopart:
	s_cmp_lg_u32 s100, 0
	s_cselect_b32 s8, 4, s4
	v_readlane_b32 s10, v254, 53
	v_readlane_b32 s11, v254, 54
	s_mul_i32 s8, s8, 0xc000
	s_add_u32 s10, s10, s8
	s_addc_u32 s11, s11, 0
	s_add_u32 s12, s10, 0x7000
	s_addc_u32 s13, s11, 0
	global_load_dwordx4 v[96:99], v176, s[12:13] offset:-4096
	global_load_dwordx4 v[100:103], v176, s[12:13] offset:-3072
	global_load_dwordx4 v[104:107], v176, s[12:13] offset:-2048
	global_load_dwordx4 v[108:111], v176, s[12:13] offset:-1024
	global_load_dwordx4 v[112:115], v176, s[12:13] offset:0
	global_load_dwordx4 v[116:119], v176, s[12:13] offset:1024
	global_load_dwordx4 v[120:123], v176, s[12:13] offset:2048
	global_load_dwordx4 v[124:127], v176, s[12:13] offset:3072
	s_add_u32 s12, s10, 0x9000
	s_addc_u32 s13, s11, 0
	global_load_dwordx4 v[128:131], v176, s[12:13] offset:-4096
	global_load_dwordx4 v[132:135], v176, s[12:13] offset:-3072
	global_load_dwordx4 v[136:139], v176, s[12:13] offset:-2048
	global_load_dwordx4 v[140:143], v176, s[12:13] offset:-1024
	global_load_dwordx4 v[144:147], v176, s[12:13] offset:0
	global_load_dwordx4 v[148:151], v176, s[12:13] offset:1024
	global_load_dwordx4 v[152:155], v176, s[12:13] offset:2048
	global_load_dwordx4 v[156:159], v176, s[12:13] offset:3072
	s_mov_b32 s3, s2

.Lnrm_p7_exit:
.LBB0_1325:
	s_waitcnt vmcnt(0)
	s_barrier
	s_mov_b64 s[2:3], exec
	v_readlane_b32 s4, v253, 42
	v_readlane_b32 s5, v253, 43
	s_and_b64 s[4:5], s[2:3], s[4:5]
	s_movk_i32 s92, 0x2c00
	s_mov_b64 exec, s[4:5]
	s_cbranch_execz .LBB0_1369
	v_readlane_b32 s56, v253, 39
	v_readlane_b32 s4, v254, 44
	v_readlane_b32 s57, v253, 40
	v_readlane_b32 s33, v253, 41
	v_mov_b32_e32 v0, s4
	s_waitcnt vmcnt(0) expcnt(0) lgkmcnt(0)
	ds_read_b32 v2, v0
	v_readlane_b32 s4, v254, 45
	s_waitcnt lgkmcnt(0)
	v_cmp_ne_u32_e32 vcc, 0, v2
	v_mov_b32_e32 v0, s4
	ds_read_b32 v0, v0
	s_cbranch_vccnz .LBB0_1340
	s_add_u32 s4, s56, 0x1000
	s_addc_u32 s5, s57, 0
	s_add_u32 s6, s56, 0x1100
	s_addc_u32 s7, s57, 0
	s_add_u32 s8, s56, 0x1200
	s_addc_u32 s9, s57, 0
	s_add_u32 s10, s56, 0x1300
	s_addc_u32 s11, s57, 0
	s_mov_b32 s30, 1
	s_mov_b64 s[12:13], 0
	s_branch .LBB0_1330

	.amdhsa_kernel _Z14fwd_megakernel6Params
		.amdhsa_group_segment_fixed_size 0
		.amdhsa_private_segment_fixed_size 0
		.amdhsa_kernarg_size 480
		.amdhsa_user_sgpr_count 2
		.amdhsa_user_sgpr_dispatch_ptr 0
		.amdhsa_user_sgpr_queue_ptr 0
		.amdhsa_user_sgpr_kernarg_segment_ptr 1
		.amdhsa_user_sgpr_dispatch_id 0
		.amdhsa_user_sgpr_kernarg_preload_length 0
		.amdhsa_user_sgpr_kernarg_preload_offset 0
		.amdhsa_user_sgpr_private_segment_size 0
		.amdhsa_uses_dynamic_stack 0
		.amdhsa_enable_private_segment 0
		.amdhsa_system_sgpr_workgroup_id_x 1
		.amdhsa_system_sgpr_workgroup_id_y 0
		.amdhsa_system_sgpr_workgroup_id_z 0
		.amdhsa_system_sgpr_workgroup_info 0
		.amdhsa_system_vgpr_workitem_id 2
		.amdhsa_next_free_vgpr 256
		.amdhsa_next_free_sgpr 102
		.amdhsa_accum_offset 256
		.amdhsa_reserve_vcc 1
		.amdhsa_float_round_mode_32 0
		.amdhsa_float_round_mode_16_64 0
		.amdhsa_float_denorm_mode_32 3
		.amdhsa_float_denorm_mode_16_64 3
		.amdhsa_dx10_clamp 1
		.amdhsa_ieee_mode 1
		.amdhsa_fp16_overflow 0
		.amdhsa_tg_split 0
		.amdhsa_exception_fp_ieee_invalid_op 0
		.amdhsa_exception_fp_denorm_src 0
		.amdhsa_exception_fp_ieee_div_zero 0
		.amdhsa_exception_fp_ieee_overflow 0
		.amdhsa_exception_fp_ieee_underflow 0
		.amdhsa_exception_fp_ieee_inexact 0
		.amdhsa_exception_int_div_zero 0
	.end_amdhsa_kernel

amdhsa.kernels:
  - .agpr_count:     0
    .args:
      - .offset:         0
        .size:           224
        .value_kind:     by_value
      - .offset:         224
        .size:           4
        .value_kind:     hidden_block_count_x
      - .offset:         228
        .size:           4
        .value_kind:     hidden_block_count_y
      - .offset:         232
        .size:           4
        .value_kind:     hidden_block_count_z
      - .offset:         236
        .size:           2
        .value_kind:     hidden_group_size_x
      - .offset:         238
        .size:           2
        .value_kind:     hidden_group_size_y
      - .offset:         240
        .size:           2
        .value_kind:     hidden_group_size_z
      - .offset:         242
        .size:           2
        .value_kind:     hidden_remainder_x
      - .offset:         244
        .size:           2
        .value_kind:     hidden_remainder_y
      - .offset:         246
        .size:           2
        .value_kind:     hidden_remainder_z
      - .offset:         264
        .size:           8
        .value_kind:     hidden_global_offset_x
      - .offset:         272
        .size:           8
        .value_kind:     hidden_global_offset_y
      - .offset:         280
        .size:           8
        .value_kind:     hidden_global_offset_z
      - .offset:         288
        .size:           2
        .value_kind:     hidden_grid_dims
      - .offset:         312
        .size:           8
        .value_kind:     hidden_multigrid_sync_arg
      - .offset:         344
        .size:           4
        .value_kind:     hidden_dynamic_lds_size
    .group_segment_fixed_size: 0
    .kernarg_segment_align: 8
    .kernarg_segment_size: 480
    .language:       OpenCL C
    .language_version:
      - 2
      - 0
    .max_flat_workgroup_size: 512
    .name:           _Z14fwd_megakernel6Params
    .private_segment_fixed_size: 0
    .sgpr_count:     108
    .sgpr_spill_count: 133
    .symbol:         _Z14fwd_megakernel6Params.kd
    .uniform_work_group_size: 1
    .uses_dynamic_stack: false
    .vgpr_count:     256
    .vgpr_spill_count: 0
    .wavefront_size: 64
